# phase-2 load rebalancing: S5 carry scan moved from workgroups 0..31 to 224..255 (off the sample-conv path); prompt conv early vmcnt(0) between row loads and weight loads removed
# speedup vs baseline: 1.0089x; 1.0031x over previous
.LBB0_629:
	v_readlane_b32 s1, v239, 41
	s_ashr_i32 s0, s18, 31
	s_lshr_b32 s0, s0, 25
	v_mov_b32_e32 v2, s1
	ds_read2_b64 v[6:9], v2 offset1:1
	s_add_i32 s0, s18, s0
	s_ashr_i32 s14, s0, 7
	s_and_b32 s0, s0, 0xffffff80
	s_sub_i32 s22, s18, s0
	v_readlane_b32 s0, v239, 42
	s_lshl_b32 s19, s22, 4
	s_waitcnt lgkmcnt(0)
	v_readfirstlane_b32 s1, v7
	v_mov_b32_e32 v2, s0
	v_readfirstlane_b32 s0, v6
	v_mov_b32_e32 v6, v0
	ds_read2_b64 v[2:5], v2 offset1:1
	s_add_u32 s0, s0, s21
	v_lshlrev_b32_e32 v6, 1, v6
	v_ashrrev_i32_e32 v7, 31, v6
	s_addc_u32 s1, s1, s20
	v_readfirstlane_b32 s15, v9
	v_readfirstlane_b32 s23, v8
	v_lshlrev_b64 v[8:9], 2, v[6:7]
	s_lshl_b64 s[10:11], s[38:39], 2
	v_lshl_add_u64 v[60:61], s[0:1], 0, v[8:9]
	s_add_u32 s0, s23, s10
	s_addc_u32 s1, s15, s11
	s_ashr_i32 s15, s14, 31
	s_max_i32 s23, s19, 30
	v_lshl_add_u64 v[8:9], s[0:1], 0, v[8:9]
	s_lshl_b64 s[0:1], s[14:15], 11
	s_sub_i32 s23, s23, 30
	s_add_u32 s23, s0, s23
	s_addc_u32 s28, s1, 0
	s_mulk_i32 s28, 0x7000
	s_mul_hi_u32 s29, s23, 0x7000
	s_add_i32 s29, s29, s28
	s_mulk_i32 s23, 0x7000
	s_add_u32 s28, s92, s23
	s_addc_u32 s29, s93, s29
	s_max_i32 s23, s19, 29
	s_sub_i32 s23, s23, 29
	v_lshlrev_b64 v[76:77], 1, v[6:7]
	s_add_u32 s23, s0, s23
	v_lshl_add_u64 v[10:11], s[28:29], 0, v[76:77]
	s_addc_u32 s28, s1, 0
	s_mulk_i32 s28, 0x7000
	s_mul_hi_u32 s29, s23, 0x7000
	s_add_i32 s29, s29, s28
	s_mulk_i32 s23, 0x7000
	s_add_u32 s28, s92, s23
	s_addc_u32 s29, s93, s29
	s_max_i32 s23, s19, 28
	s_sub_i32 s23, s23, 28
	s_add_u32 s23, s0, s23
	v_lshl_add_u64 v[14:15], s[28:29], 0, v[76:77]
	s_addc_u32 s28, s1, 0
	s_mulk_i32 s28, 0x7000
	s_mul_hi_u32 s29, s23, 0x7000
	s_add_i32 s29, s29, s28
	s_mulk_i32 s23, 0x7000
	s_add_u32 s28, s92, s23
	s_addc_u32 s29, s93, s29
	s_max_i32 s23, s19, 27
	s_sub_i32 s23, s23, 27
	v_add_co_u32_e32 v12, vcc, s5, v10
	s_add_u32 s23, s0, s23
	s_nop 0
	v_addc_co_u32_e32 v13, vcc, 0, v11, vcc
	v_lshl_add_u64 v[22:23], s[28:29], 0, v[76:77]
	s_addc_u32 s28, s1, 0
	v_add_co_u32_e32 v10, vcc, s87, v10
	s_mulk_i32 s28, 0x7000
	s_mul_hi_u32 s29, s23, 0x7000
	v_addc_co_u32_e32 v11, vcc, 0, v11, vcc
	s_add_i32 s29, s29, s28
	s_mulk_i32 s23, 0x7000
	v_add_co_u32_e32 v16, vcc, s5, v14
	s_add_u32 s28, s92, s23
	s_nop 0
	v_addc_co_u32_e32 v17, vcc, 0, v15, vcc
	s_addc_u32 s29, s93, s29
	s_max_i32 s23, s19, 26
	v_add_co_u32_e32 v14, vcc, s87, v14
	s_sub_i32 s23, s23, 26
	s_nop 0
	v_addc_co_u32_e32 v15, vcc, 0, v15, vcc
	s_add_u32 s23, s0, s23
	v_add_co_u32_e32 v24, vcc, s5, v22
	v_lshl_add_u64 v[26:27], s[28:29], 0, v[76:77]
	s_addc_u32 s28, s1, 0
	v_addc_co_u32_e32 v25, vcc, 0, v23, vcc
	s_mulk_i32 s28, 0x7000
	s_mul_hi_u32 s29, s23, 0x7000
	v_add_co_u32_e32 v22, vcc, s87, v22
	s_add_i32 s29, s29, s28
	s_mulk_i32 s23, 0x7000
	v_addc_co_u32_e32 v23, vcc, 0, v23, vcc
	s_add_u32 s28, s92, s23
	v_add_co_u32_e32 v28, vcc, s5, v26
	s_addc_u32 s29, s93, s29
	s_max_i32 s23, s19, 25
	v_addc_co_u32_e32 v29, vcc, 0, v27, vcc
	s_sub_i32 s23, s23, 25
	v_add_co_u32_e32 v26, vcc, s87, v26
	s_add_u32 s23, s0, s23
	s_nop 0
	v_addc_co_u32_e32 v27, vcc, 0, v27, vcc
	global_load_dword v84, v[12:13], off offset:2048
	global_load_dword v85, v[10:11], off
	global_load_dword v83, v[16:17], off offset:2048
	global_load_dword v82, v[14:15], off
	global_load_dword v79, v[24:25], off offset:2048
	global_load_dword v80, v[22:23], off
	global_load_dword v78, v[28:29], off offset:2048
	global_load_dword v81, v[26:27], off
	v_lshl_add_u64 v[10:11], s[28:29], 0, v[76:77]
	s_addc_u32 s28, s1, 0
	s_mulk_i32 s28, 0x7000
	s_mul_hi_u32 s29, s23, 0x7000
	s_add_i32 s29, s29, s28
	s_mulk_i32 s23, 0x7000
	s_add_u32 s28, s92, s23
	s_addc_u32 s29, s93, s29
	s_max_i32 s23, s19, 24
	s_sub_i32 s23, s23, 24
	s_add_u32 s23, s0, s23
	v_lshl_add_u64 v[14:15], s[28:29], 0, v[76:77]
	s_addc_u32 s28, s1, 0
	s_mulk_i32 s28, 0x7000
	s_mul_hi_u32 s29, s23, 0x7000
	s_add_i32 s29, s29, s28
	s_mulk_i32 s23, 0x7000
	s_add_u32 s28, s92, s23
	v_add_co_u32_e32 v12, vcc, s5, v10
	s_addc_u32 s29, s93, s29
	s_max_i32 s23, s19, 23
	v_addc_co_u32_e32 v13, vcc, 0, v11, vcc
	s_sub_i32 s23, s23, 23
	v_add_co_u32_e32 v10, vcc, s87, v10
	s_add_u32 s23, s0, s23
	s_nop 0
	v_addc_co_u32_e32 v11, vcc, 0, v11, vcc
	v_lshl_add_u64 v[22:23], s[28:29], 0, v[76:77]
	s_addc_u32 s28, s1, 0
	v_add_co_u32_e32 v16, vcc, s5, v14
	s_mulk_i32 s28, 0x7000
	s_mul_hi_u32 s29, s23, 0x7000
	v_addc_co_u32_e32 v17, vcc, 0, v15, vcc
	s_add_i32 s29, s29, s28
	s_mulk_i32 s23, 0x7000
	v_add_co_u32_e32 v14, vcc, s87, v14
	s_add_u32 s28, s92, s23
	s_nop 0
	v_addc_co_u32_e32 v15, vcc, 0, v15, vcc
	s_addc_u32 s29, s93, s29
	s_max_i32 s23, s19, 22
	v_add_co_u32_e32 v24, vcc, s5, v22
	s_sub_i32 s23, s23, 22
	s_nop 0
	v_addc_co_u32_e32 v25, vcc, 0, v23, vcc
	s_add_u32 s23, s0, s23
	v_add_co_u32_e32 v22, vcc, s87, v22
	v_lshl_add_u64 v[26:27], s[28:29], 0, v[76:77]
	s_addc_u32 s28, s1, 0
	v_addc_co_u32_e32 v23, vcc, 0, v23, vcc
	s_mulk_i32 s28, 0x7000
	s_mul_hi_u32 s29, s23, 0x7000
	v_add_co_u32_e32 v28, vcc, s5, v26
	s_add_i32 s29, s29, s28
	s_mulk_i32 s23, 0x7000
	v_addc_co_u32_e32 v29, vcc, 0, v27, vcc
	s_add_u32 s28, s92, s23
	v_add_co_u32_e32 v26, vcc, s87, v26
	s_addc_u32 s29, s93, s29
	s_nop 0
	v_addc_co_u32_e32 v27, vcc, 0, v27, vcc
	global_load_dword v92, v[12:13], off offset:2048
	global_load_dword v93, v[10:11], off
	global_load_dword v90, v[16:17], off offset:2048
	global_load_dword v91, v[14:15], off
	global_load_dword v87, v[24:25], off offset:2048
	global_load_dword v88, v[22:23], off
	global_load_dword v86, v[28:29], off offset:2048
	global_load_dword v89, v[26:27], off
	v_lshl_add_u64 v[10:11], s[28:29], 0, v[76:77]
	v_add_co_u32_e32 v12, vcc, s5, v10
	s_movk_i32 s23, 0x5000
	s_nop 0
	v_addc_co_u32_e32 v13, vcc, 0, v11, vcc
	v_add_co_u32_e32 v10, vcc, s87, v10
	s_waitcnt lgkmcnt(0)
	v_readfirstlane_b32 s34, v4
	v_addc_co_u32_e32 v11, vcc, 0, v11, vcc
	global_load_dword v96, v[12:13], off offset:2048
	global_load_dword v97, v[10:11], off
	flat_load_dwordx2 v[12:13], v[60:61]
	v_add_co_u32_e32 v10, vcc, s17, v60
	s_nop 1
	v_addc_co_u32_e32 v11, vcc, 0, v61, vcc
	v_add_co_u32_e32 v16, vcc, s5, v60
	s_nop 1
	v_addc_co_u32_e32 v17, vcc, 0, v61, vcc
	v_add_co_u32_e32 v22, vcc, s87, v60
	s_nop 1
	v_addc_co_u32_e32 v23, vcc, 0, v61, vcc
	v_add_co_u32_e32 v24, vcc, s6, v60
	s_nop 1
	v_addc_co_u32_e32 v25, vcc, 0, v61, vcc
	flat_load_dwordx2 v[14:15], v[10:11]
	s_nop 0
	flat_load_dwordx2 v[16:17], v[16:17]
	s_nop 0
	flat_load_dwordx2 v[22:23], v[22:23]
	s_nop 0
	flat_load_dwordx2 v[24:25], v[24:25]
	v_add_co_u32_e32 v10, vcc, s23, v60
	s_mov_b32 s23, 0x8000
	s_nop 0
	v_addc_co_u32_e32 v11, vcc, 0, v61, vcc
	v_add_co_u32_e32 v26, vcc, s7, v60
	s_nop 1
	v_addc_co_u32_e32 v27, vcc, 0, v61, vcc
	v_add_co_u32_e32 v28, vcc, s16, v60
	s_nop 1
	v_addc_co_u32_e32 v29, vcc, 0, v61, vcc
	v_add_co_u32_e32 v30, vcc, s23, v60
	s_max_i32 s23, s19, 21
	s_sub_i32 s23, s23, 21
	s_add_u32 s23, s0, s23
	s_addc_u32 s28, s1, 0
	s_mulk_i32 s28, 0x7000
	s_mul_hi_u32 s29, s23, 0x7000
	s_add_i32 s29, s29, s28
	s_mulk_i32 s23, 0x7000
	s_add_u32 s28, s92, s23
	s_addc_u32 s29, s93, s29
	v_addc_co_u32_e32 v31, vcc, 0, v61, vcc
	flat_load_dwordx2 v[42:43], v[10:11]
	flat_load_dwordx2 v[44:45], v[26:27]
	flat_load_dwordx2 v[46:47], v[28:29]
	flat_load_dwordx2 v[48:49], v[30:31]
	flat_load_dwordx2 v[58:59], v[8:9]
	v_lshl_add_u64 v[8:9], s[28:29], 0, v[76:77]
	v_add_co_u32_e32 v10, vcc, s5, v8
	s_mov_b32 s23, 0x9000
	s_nop 0
	v_addc_co_u32_e32 v11, vcc, 0, v9, vcc
	v_add_co_u32_e32 v8, vcc, s87, v8
	s_nop 1
	v_addc_co_u32_e32 v9, vcc, 0, v9, vcc
	global_load_dword v94, v[10:11], off offset:2048
	global_load_dword v95, v[8:9], off
	v_add_co_u32_e32 v8, vcc, s23, v60
	s_max_i32 s23, s19, 20
	s_sub_i32 s23, s23, 20
	s_add_u32 s23, s0, s23
	s_addc_u32 s28, s1, 0
	s_mulk_i32 s28, 0x7000
	s_mul_hi_u32 s29, s23, 0x7000
	s_add_i32 s29, s29, s28
	s_mulk_i32 s23, 0x7000
	s_add_u32 s28, s92, s23
	s_addc_u32 s29, s93, s29
	s_max_i32 s23, s19, 19
	s_sub_i32 s23, s23, 19
	s_add_u32 s23, s0, s23
	v_lshl_add_u64 v[10:11], s[28:29], 0, v[76:77]
	s_addc_u32 s28, s1, 0
	s_mulk_i32 s28, 0x7000
	s_mul_hi_u32 s29, s23, 0x7000
	s_add_i32 s29, s29, s28
	s_mulk_i32 s23, 0x7000
	s_add_u32 s28, s92, s23
	s_addc_u32 s29, s93, s29
	s_max_i32 s23, s19, 18
	s_sub_i32 s23, s23, 18
	s_add_u32 s23, s0, s23
	v_lshl_add_u64 v[28:29], s[28:29], 0, v[76:77]
	s_addc_u32 s28, s1, 0
	s_mulk_i32 s28, 0x7000
	s_mul_hi_u32 s29, s23, 0x7000
	s_add_i32 s29, s29, s28
	s_mulk_i32 s23, 0x7000
	s_add_u32 s28, s92, s23
	s_addc_u32 s29, s93, s29
	s_max_i32 s23, s19, 17
	v_addc_co_u32_e32 v9, vcc, 0, v61, vcc
	s_sub_i32 s23, s23, 17
	v_add_co_u32_e32 v26, vcc, s5, v10
	s_add_u32 s23, s0, s23
	s_nop 0
	v_addc_co_u32_e32 v27, vcc, 0, v11, vcc
	v_lshl_add_u64 v[32:33], s[28:29], 0, v[76:77]
	s_addc_u32 s28, s1, 0
	v_add_co_u32_e32 v10, vcc, s87, v10
	s_mulk_i32 s28, 0x7000
	s_mul_hi_u32 s29, s23, 0x7000
	v_addc_co_u32_e32 v11, vcc, 0, v11, vcc
	s_add_i32 s29, s29, s28
	s_mulk_i32 s23, 0x7000
	v_add_co_u32_e32 v30, vcc, s5, v28
	s_add_u32 s28, s92, s23
	s_nop 0
	v_addc_co_u32_e32 v31, vcc, 0, v29, vcc
	s_addc_u32 s29, s93, s29
	s_max_i32 s23, s19, 16
	v_add_co_u32_e32 v28, vcc, s87, v28
	s_add_i32 s23, s23, -16
	s_nop 0
	v_addc_co_u32_e32 v29, vcc, 0, v29, vcc
	s_add_u32 s23, s0, s23
	v_add_co_u32_e32 v34, vcc, s5, v32
	v_lshl_add_u64 v[36:37], s[28:29], 0, v[76:77]
	s_addc_u32 s28, s1, 0
	v_addc_co_u32_e32 v35, vcc, 0, v33, vcc
	s_mulk_i32 s28, 0x7000
	s_mul_hi_u32 s29, s23, 0x7000
	v_add_co_u32_e32 v32, vcc, s87, v32
	s_add_i32 s29, s29, s28
	s_mulk_i32 s23, 0x7000
	v_addc_co_u32_e32 v33, vcc, 0, v33, vcc
	s_add_u32 s28, s92, s23
	v_add_co_u32_e32 v38, vcc, s5, v36
	s_addc_u32 s29, s93, s29
	s_max_i32 s23, s19, 15
	v_addc_co_u32_e32 v39, vcc, 0, v37, vcc
	s_add_i32 s23, s23, -15
	v_add_co_u32_e32 v36, vcc, s87, v36
	s_add_u32 s23, s0, s23
	flat_load_dwordx2 v[8:9], v[8:9]
	v_addc_co_u32_e32 v37, vcc, 0, v37, vcc
	global_load_dword v108, v[26:27], off offset:2048
	global_load_dword v109, v[10:11], off
	global_load_dword v106, v[30:31], off offset:2048
	global_load_dword v107, v[28:29], off
	global_load_dword v105, v[34:35], off offset:2048
	global_load_dword v104, v[32:33], off
	global_load_dword v102, v[38:39], off offset:2048
	global_load_dword v103, v[36:37], off
	v_lshl_add_u64 v[10:11], s[28:29], 0, v[76:77]
	s_addc_u32 s28, s1, 0
	s_mulk_i32 s28, 0x7000
	s_mul_hi_u32 s29, s23, 0x7000
	s_add_i32 s29, s29, s28
	s_mulk_i32 s23, 0x7000
	s_add_u32 s28, s92, s23
	s_addc_u32 s29, s93, s29
	s_max_i32 s23, s19, 14
	s_add_i32 s23, s23, -14
	s_add_u32 s23, s0, s23
	v_lshl_add_u64 v[28:29], s[28:29], 0, v[76:77]
	s_addc_u32 s28, s1, 0
	s_mulk_i32 s28, 0x7000
	s_mul_hi_u32 s29, s23, 0x7000
	s_add_i32 s29, s29, s28
	s_mulk_i32 s23, 0x7000
	s_add_u32 s28, s92, s23
	s_addc_u32 s29, s93, s29
	s_max_i32 s23, s19, 13
	s_add_i32 s23, s23, -13
	v_add_co_u32_e32 v26, vcc, s5, v10
	s_add_u32 s23, s0, s23
	s_nop 0
	v_addc_co_u32_e32 v27, vcc, 0, v11, vcc
	v_lshl_add_u64 v[32:33], s[28:29], 0, v[76:77]
	s_addc_u32 s28, s1, 0
	v_add_co_u32_e32 v10, vcc, s87, v10
	s_mulk_i32 s28, 0x7000
	s_mul_hi_u32 s29, s23, 0x7000
	v_addc_co_u32_e32 v11, vcc, 0, v11, vcc
	s_add_i32 s29, s29, s28
	s_mulk_i32 s23, 0x7000
	v_add_co_u32_e32 v30, vcc, s5, v28
	s_add_u32 s28, s92, s23
	s_nop 0
	v_addc_co_u32_e32 v31, vcc, 0, v29, vcc
	s_addc_u32 s29, s93, s29
	s_max_i32 s23, s19, 12
	v_add_co_u32_e32 v28, vcc, s87, v28
	s_add_i32 s23, s23, -12
	s_nop 0
	v_addc_co_u32_e32 v29, vcc, 0, v29, vcc
	s_add_u32 s23, s0, s23
	v_add_co_u32_e32 v34, vcc, s5, v32
	v_lshl_add_u64 v[36:37], s[28:29], 0, v[76:77]
	s_addc_u32 s28, s1, 0
	v_addc_co_u32_e32 v35, vcc, 0, v33, vcc
	s_mulk_i32 s28, 0x7000
	s_mul_hi_u32 s29, s23, 0x7000
	v_add_co_u32_e32 v32, vcc, s87, v32
	s_add_i32 s29, s29, s28
	s_mulk_i32 s23, 0x7000
	v_addc_co_u32_e32 v33, vcc, 0, v33, vcc
	s_add_u32 s28, s92, s23
	v_add_co_u32_e32 v38, vcc, s5, v36
	s_addc_u32 s29, s93, s29
	s_max_i32 s23, s19, 11
	v_addc_co_u32_e32 v39, vcc, 0, v37, vcc
	s_add_i32 s23, s23, -11
	v_add_co_u32_e32 v36, vcc, s87, v36
	s_add_u32 s23, s0, s23
	s_nop 0
	v_addc_co_u32_e32 v37, vcc, 0, v37, vcc
	global_load_dword v116, v[26:27], off offset:2048
	global_load_dword v117, v[10:11], off
	global_load_dword v114, v[30:31], off offset:2048
	global_load_dword v115, v[28:29], off
	global_load_dword v111, v[34:35], off offset:2048
	global_load_dword v112, v[32:33], off
	global_load_dword v110, v[38:39], off offset:2048
	global_load_dword v113, v[36:37], off
	v_lshl_add_u64 v[10:11], s[28:29], 0, v[76:77]
	s_addc_u32 s28, s1, 0
	s_mulk_i32 s28, 0x7000
	s_mul_hi_u32 s29, s23, 0x7000
	v_add_co_u32_e32 v26, vcc, s5, v10
	s_add_i32 s29, s29, s28
	s_mulk_i32 s23, 0x7000
	v_addc_co_u32_e32 v27, vcc, 0, v11, vcc
	s_add_u32 s28, s92, s23
	v_add_co_u32_e32 v10, vcc, s87, v10
	s_addc_u32 s29, s93, s29
	s_nop 0
	v_addc_co_u32_e32 v11, vcc, 0, v11, vcc
	v_lshl_add_u64 v[28:29], s[28:29], 0, v[76:77]
	v_add_co_u32_e32 v30, vcc, s5, v28
	s_mov_b32 s23, 0xa000
	s_nop 0
	v_addc_co_u32_e32 v31, vcc, 0, v29, vcc
	v_add_co_u32_e32 v28, vcc, s87, v28
	s_nop 1
	v_addc_co_u32_e32 v29, vcc, 0, v29, vcc
	global_load_dword v119, v[26:27], off offset:2048
	global_load_dword v120, v[10:11], off
	global_load_dword v118, v[30:31], off offset:2048
	global_load_dword v121, v[28:29], off
	v_add_co_u32_e32 v10, vcc, s23, v60
	s_mov_b32 s23, 0xb000
	s_nop 0
	v_addc_co_u32_e32 v11, vcc, 0, v61, vcc
	v_add_co_u32_e32 v26, vcc, s23, v60
	s_mov_b32 s23, 0xd000
	s_nop 0
	v_addc_co_u32_e32 v27, vcc, 0, v61, vcc
	v_add_co_u32_e32 v28, vcc, s2, v60
	s_nop 1
	v_addc_co_u32_e32 v29, vcc, 0, v61, vcc
	v_add_co_u32_e32 v30, vcc, s23, v60
	s_mov_b32 s23, 0xe000
	s_nop 0
	v_addc_co_u32_e32 v31, vcc, 0, v61, vcc
	flat_load_dwordx2 v[34:35], v[10:11]
	flat_load_dwordx2 v[36:37], v[26:27]
	flat_load_dwordx2 v[38:39], v[28:29]
	flat_load_dwordx2 v[40:41], v[30:31]
	v_add_co_u32_e32 v10, vcc, s23, v60
	s_mov_b32 s23, 0xf000
	s_nop 0
	v_addc_co_u32_e32 v11, vcc, 0, v61, vcc
	v_add_co_u32_e32 v26, vcc, s23, v60
	s_mov_b32 s23, 0x11000
	s_nop 0
	v_addc_co_u32_e32 v27, vcc, 0, v61, vcc
	v_add_co_u32_e32 v28, vcc, s97, v60
	s_nop 1
	v_addc_co_u32_e32 v29, vcc, 0, v61, vcc
	v_add_co_u32_e32 v30, vcc, s23, v60
	s_mov_b32 s23, 0x12000
	s_nop 0
	v_addc_co_u32_e32 v31, vcc, 0, v61, vcc
	flat_load_dwordx2 v[62:63], v[10:11]
	flat_load_dwordx2 v[64:65], v[26:27]
	flat_load_dwordx2 v[66:67], v[28:29]
	flat_load_dwordx2 v[68:69], v[30:31]
	v_add_co_u32_e32 v10, vcc, s23, v60
	s_mov_b32 s23, 0x13000
	s_nop 0
	v_addc_co_u32_e32 v11, vcc, 0, v61, vcc
	v_add_co_u32_e32 v26, vcc, s23, v60
	s_max_i32 s23, s19, 10
	s_add_i32 s23, s23, -10
	s_add_u32 s23, s0, s23
	s_addc_u32 s28, s1, 0
	s_mulk_i32 s28, 0x7000
	s_mul_hi_u32 s29, s23, 0x7000
	s_add_i32 s29, s29, s28
	s_mulk_i32 s23, 0x7000
	s_add_u32 s28, s92, s23
	s_addc_u32 s29, s93, s29
	s_max_i32 s23, s19, 9
	s_add_i32 s23, s23, -9
	s_add_u32 s23, s0, s23
	v_addc_co_u32_e32 v27, vcc, 0, v61, vcc
	flat_load_dwordx2 v[72:73], v[10:11]
	flat_load_dwordx2 v[74:75], v[26:27]
	v_lshl_add_u64 v[10:11], s[28:29], 0, v[76:77]
	s_addc_u32 s28, s1, 0
	s_mulk_i32 s28, 0x7000
	s_mul_hi_u32 s29, s23, 0x7000
	s_add_i32 s29, s29, s28
	s_mulk_i32 s23, 0x7000
	s_add_u32 s28, s92, s23
	v_add_co_u32_e32 v26, vcc, s5, v10
	s_addc_u32 s29, s93, s29
	s_max_i32 s23, s19, 8
	v_addc_co_u32_e32 v27, vcc, 0, v11, vcc
	s_add_i32 s23, s23, -8
	v_add_co_u32_e32 v10, vcc, s87, v10
	s_add_u32 s23, s0, s23
	s_nop 0
	v_addc_co_u32_e32 v11, vcc, 0, v11, vcc
	global_load_dword v136, v[26:27], off offset:2048
	global_load_dword v138, v[10:11], off
	v_lshl_add_u64 v[26:27], s[28:29], 0, v[76:77]
	s_addc_u32 s28, s1, 0
	s_mulk_i32 s28, 0x7000
	s_mul_hi_u32 s29, s23, 0x7000
	s_add_i32 s29, s29, s28
	s_mulk_i32 s23, 0x7000
	s_add_u32 s28, s92, s23
	s_addc_u32 s29, s93, s29
	s_max_i32 s23, s19, 7
	s_add_i32 s23, s23, -7
	s_add_u32 s23, s0, s23
	v_lshl_add_u64 v[30:31], s[28:29], 0, v[76:77]
	s_addc_u32 s28, s1, 0
	s_mulk_i32 s28, 0x7000
	s_mul_hi_u32 s29, s23, 0x7000
	s_add_i32 s29, s29, s28
	s_mulk_i32 s23, 0x7000
	s_add_u32 s28, s92, s23
	s_addc_u32 s29, s93, s29
	s_max_i32 s23, s19, 6
	s_add_i32 s23, s23, -6
	s_add_u32 s23, s0, s23
	v_lshl_add_u64 v[122:123], s[28:29], 0, v[76:77]
	s_addc_u32 s28, s1, 0
	s_mulk_i32 s28, 0x7000
	s_mul_hi_u32 s29, s23, 0x7000
	s_add_i32 s29, s29, s28
	s_mulk_i32 s23, 0x7000
	s_add_u32 s28, s92, s23
	s_addc_u32 s29, s93, s29
	s_max_i32 s23, s19, 5
	s_add_i32 s23, s23, -5
	s_add_u32 s23, s0, s23
	v_lshl_add_u64 v[130:131], s[28:29], 0, v[76:77]
	s_addc_u32 s28, s1, 0
	s_mulk_i32 s28, 0x7000
	s_mul_hi_u32 s29, s23, 0x7000
	s_add_i32 s29, s29, s28
	s_mulk_i32 s23, 0x7000
	s_add_u32 s28, s92, s23
	s_addc_u32 s29, s93, s29
	s_max_i32 s23, s19, 4
	s_add_i32 s23, s23, -4
	s_add_u32 s23, s0, s23
	v_lshl_add_u64 v[132:133], s[28:29], 0, v[76:77]
	s_addc_u32 s28, s1, 0
	s_mulk_i32 s28, 0x7000
	s_mul_hi_u32 s29, s23, 0x7000
	s_add_i32 s29, s29, s28
	s_mulk_i32 s23, 0x7000
	s_add_u32 s28, s92, s23
	s_addc_u32 s29, s93, s29
	s_max_i32 s23, s19, 3
	s_add_i32 s23, s23, -3
	s_add_u32 s23, s0, s23
	v_lshl_add_u64 v[134:135], s[28:29], 0, v[76:77]
	s_addc_u32 s28, s1, 0
	s_mulk_i32 s28, 0x7000
	s_mul_hi_u32 s29, s23, 0x7000
	s_add_i32 s29, s29, s28
	s_mulk_i32 s23, 0x7000
	s_add_u32 s28, s92, s23
	s_addc_u32 s29, s93, s29
	s_max_i32 s23, s19, 2
	s_add_i32 s23, s23, -2
	s_add_u32 s23, s0, s23
	v_lshl_add_u64 v[140:141], s[28:29], 0, v[76:77]
	s_addc_u32 s28, s1, 0
	s_mulk_i32 s28, 0x7000
	s_mul_hi_u32 s29, s23, 0x7000
	s_add_i32 s29, s29, s28
	s_mulk_i32 s23, 0x7000
	s_add_u32 s28, s92, s23
	s_addc_u32 s29, s93, s29
	s_max_i32 s23, s19, 1
	s_add_i32 s23, s23, -1
	s_add_u32 s23, s0, s23
	v_add_co_u32_e32 v10, vcc, s8, v60
	v_lshl_add_u64 v[146:147], s[28:29], 0, v[76:77]
	s_addc_u32 s28, s1, 0
	v_addc_co_u32_e32 v11, vcc, 0, v61, vcc
	s_mulk_i32 s28, 0x7000
	s_mul_hi_u32 s29, s23, 0x7000
	v_add_co_u32_e32 v28, vcc, s5, v26
	s_add_i32 s29, s29, s28
	s_mulk_i32 s23, 0x7000
	v_addc_co_u32_e32 v29, vcc, 0, v27, vcc
	s_add_u32 s28, s92, s23
	v_add_co_u32_e32 v26, vcc, s87, v26
	s_addc_u32 s29, s93, s29
	s_max_i32 s23, s19, 0
	v_addc_co_u32_e32 v27, vcc, 0, v27, vcc
	s_add_u32 s23, s0, s23
	v_add_co_u32_e32 v32, vcc, s5, v30
	v_lshl_add_u64 v[148:149], s[28:29], 0, v[76:77]
	s_addc_u32 s28, s1, 0
	v_addc_co_u32_e32 v33, vcc, 0, v31, vcc
	s_mulk_i32 s28, 0x7000
	s_mul_hi_u32 s29, s23, 0x7000
	v_add_co_u32_e32 v30, vcc, s87, v30
	s_add_i32 s29, s29, s28
	s_mulk_i32 s23, 0x7000
	v_addc_co_u32_e32 v31, vcc, 0, v31, vcc
	s_add_u32 s28, s92, s23
	s_mov_b32 s23, 0x15000
	flat_load_dwordx2 v[10:11], v[10:11]
	s_nop 0
	global_load_dword v143, v[28:29], off offset:2048
	global_load_dword v144, v[26:27], off
	global_load_dword v127, v[32:33], off offset:2048
	global_load_dword v129, v[30:31], off
	v_add_co_u32_e32 v26, vcc, s23, v60
	s_mov_b32 s23, 0x17000
	s_nop 0
	v_addc_co_u32_e32 v27, vcc, 0, v61, vcc
	v_add_co_u32_e32 v28, vcc, s27, v60
	s_addc_u32 s29, s93, s29
	s_nop 0
	v_addc_co_u32_e32 v29, vcc, 0, v61, vcc
	v_add_co_u32_e32 v30, vcc, s23, v60
	s_mov_b32 s23, 0x19000
	s_nop 0
	v_addc_co_u32_e32 v31, vcc, 0, v61, vcc
	v_add_co_u32_e32 v32, vcc, s3, v60
	v_lshl_add_u64 v[150:151], s[28:29], 0, v[76:77]
	s_nop 0
	v_addc_co_u32_e32 v33, vcc, 0, v61, vcc
	v_add_co_u32_e32 v50, vcc, s23, v60
	s_mov_b32 s23, 0x1a000
	s_nop 0
	v_addc_co_u32_e32 v51, vcc, 0, v61, vcc
	v_add_co_u32_e32 v52, vcc, s23, v60
	s_mov_b32 s23, 0x1b000
	s_nop 0
	v_addc_co_u32_e32 v53, vcc, 0, v61, vcc
	v_add_co_u32_e32 v54, vcc, s23, v60
	s_mov_b32 s23, 0x1c000
	s_nop 0
	v_addc_co_u32_e32 v55, vcc, 0, v61, vcc
	v_add_co_u32_e32 v56, vcc, s23, v60
	s_mov_b32 s23, 0x1d000
	s_nop 0
	v_addc_co_u32_e32 v57, vcc, 0, v61, vcc
	v_add_co_u32_e32 v70, vcc, s23, v60
	s_mov_b32 s23, 0x1e000
	s_nop 0
	v_addc_co_u32_e32 v71, vcc, 0, v61, vcc
	v_add_co_u32_e32 v60, vcc, s23, v60
	flat_load_dwordx2 v[26:27], v[26:27]
	s_nop 0
	flat_load_dwordx2 v[28:29], v[28:29]
	s_nop 0
	flat_load_dwordx2 v[30:31], v[30:31]
	s_nop 0
	flat_load_dwordx2 v[32:33], v[32:33]
	v_addc_co_u32_e32 v61, vcc, 0, v61, vcc
	v_add_co_u32_e32 v152, vcc, s5, v122
	flat_load_dwordx2 v[50:51], v[50:51]
	s_nop 0
	flat_load_dwordx2 v[52:53], v[52:53]
	s_nop 0
	flat_load_dwordx2 v[54:55], v[54:55]
	s_nop 0
	flat_load_dwordx2 v[56:57], v[56:57]
	v_addc_co_u32_e32 v153, vcc, 0, v123, vcc
	v_add_co_u32_e32 v122, vcc, s87, v122
	flat_load_dwordx2 v[70:71], v[70:71]
	s_nop 0
	flat_load_dwordx2 v[60:61], v[60:61]
	v_addc_co_u32_e32 v123, vcc, 0, v123, vcc
	v_add_co_u32_e32 v154, vcc, s5, v130
	s_max_i32 s23, s19, -1
	s_nop 0
	v_addc_co_u32_e32 v155, vcc, 0, v131, vcc
	v_add_co_u32_e32 v130, vcc, s87, v130
	s_add_i32 s23, s23, 1
	s_nop 0
	v_addc_co_u32_e32 v131, vcc, 0, v131, vcc
	v_add_co_u32_e32 v156, vcc, s5, v132
	s_add_u32 s23, s0, s23
	s_nop 0
	v_addc_co_u32_e32 v157, vcc, 0, v133, vcc
	v_add_co_u32_e32 v132, vcc, s87, v132
	s_addc_u32 s28, s1, 0
	s_nop 0
	v_addc_co_u32_e32 v133, vcc, 0, v133, vcc
	v_add_co_u32_e32 v158, vcc, s5, v134
	s_mulk_i32 s28, 0x7000
	s_nop 0
	v_addc_co_u32_e32 v159, vcc, 0, v135, vcc
	v_add_co_u32_e32 v134, vcc, s87, v134
	s_mul_hi_u32 s29, s23, 0x7000
	s_nop 0
	v_addc_co_u32_e32 v135, vcc, 0, v135, vcc
	global_load_dword v185, v[152:153], off offset:2048
	global_load_dword v184, v[122:123], off
	global_load_dword v183, v[154:155], off offset:2048
	global_load_dword v182, v[130:131], off
	global_load_dword v181, v[156:157], off offset:2048
	global_load_dword v180, v[132:133], off
	global_load_dword v167, v[158:159], off offset:2048
	global_load_dword v168, v[134:135], off
	v_add_co_u32_e32 v122, vcc, s5, v140
	s_add_i32 s29, s29, s28
	s_nop 0
	v_addc_co_u32_e32 v123, vcc, 0, v141, vcc
	v_add_co_u32_e32 v130, vcc, s87, v140
	s_mulk_i32 s23, 0x7000
	s_nop 0
	v_addc_co_u32_e32 v131, vcc, 0, v141, vcc
	v_add_co_u32_e32 v132, vcc, s5, v146
	s_add_u32 s28, s92, s23
	s_nop 0
	v_addc_co_u32_e32 v133, vcc, 0, v147, vcc
	v_add_co_u32_e32 v134, vcc, s87, v146
	s_addc_u32 s29, s93, s29
	s_nop 0
	v_addc_co_u32_e32 v135, vcc, 0, v147, vcc
	v_add_co_u32_e32 v140, vcc, s5, v148
	s_max_i32 s23, s19, -2
	s_nop 0
	v_addc_co_u32_e32 v141, vcc, 0, v149, vcc
	v_add_co_u32_e32 v146, vcc, s87, v148
	s_add_i32 s23, s23, 2
	s_nop 0
	v_addc_co_u32_e32 v147, vcc, 0, v149, vcc
	v_add_co_u32_e32 v148, vcc, s5, v150
	s_add_u32 s23, s0, s23
	s_nop 0
	v_addc_co_u32_e32 v149, vcc, 0, v151, vcc
	v_add_co_u32_e32 v150, vcc, s87, v150
	s_nop 1
	v_addc_co_u32_e32 v151, vcc, 0, v151, vcc
	global_load_dword v179, v[122:123], off offset:2048
	global_load_dword v169, v[130:131], off
	global_load_dword v166, v[132:133], off offset:2048
	global_load_dword v165, v[134:135], off
	global_load_dword v158, v[140:141], off offset:2048
	global_load_dword v157, v[146:147], off
	s_nop 0
	global_load_dword v147, v[148:149], off offset:2048
	s_nop 0
	global_load_dword v148, v[150:151], off
	v_lshl_add_u64 v[122:123], s[28:29], 0, v[76:77]
	s_addc_u32 s28, s1, 0
	s_mulk_i32 s28, 0x7000
	s_mul_hi_u32 s29, s23, 0x7000
	s_add_i32 s29, s29, s28
	s_mulk_i32 s23, 0x7000
	s_add_u32 s28, s92, s23
	s_addc_u32 s29, s93, s29
	s_max_i32 s23, s19, -3
	s_add_i32 s23, s23, 3
	s_add_u32 s23, s0, s23
	v_lshl_add_u64 v[132:133], s[28:29], 0, v[76:77]
	s_addc_u32 s28, s1, 0
	s_mulk_i32 s28, 0x7000
	s_mul_hi_u32 s29, s23, 0x7000
	s_add_i32 s29, s29, s28
	s_mulk_i32 s23, 0x7000
	s_add_u32 s28, s92, s23
	s_addc_u32 s29, s93, s29
	s_max_i32 s23, s19, -4
	s_add_i32 s23, s23, 4
	v_add_co_u32_e32 v130, vcc, s5, v122
	s_add_u32 s23, s0, s23
	s_nop 0
	v_addc_co_u32_e32 v131, vcc, 0, v123, vcc
	v_lshl_add_u64 v[140:141], s[28:29], 0, v[76:77]
	s_addc_u32 s28, s1, 0
	v_add_co_u32_e32 v122, vcc, s87, v122
	s_mulk_i32 s28, 0x7000
	s_mul_hi_u32 s29, s23, 0x7000
	v_addc_co_u32_e32 v123, vcc, 0, v123, vcc
	s_add_i32 s29, s29, s28
	s_mulk_i32 s23, 0x7000
	v_add_co_u32_e32 v134, vcc, s5, v132
	s_add_u32 s28, s92, s23
	s_nop 0
	v_addc_co_u32_e32 v135, vcc, 0, v133, vcc
	s_addc_u32 s29, s93, s29
	s_max_i32 s23, s19, -5
	v_add_co_u32_e32 v132, vcc, s87, v132
	s_add_i32 s23, s23, 5
	s_nop 0
	v_addc_co_u32_e32 v133, vcc, 0, v133, vcc
	s_add_u32 s23, s0, s23
	v_add_co_u32_e32 v150, vcc, s5, v140
	v_lshl_add_u64 v[152:153], s[28:29], 0, v[76:77]
	s_addc_u32 s28, s1, 0
	v_addc_co_u32_e32 v151, vcc, 0, v141, vcc
	s_mulk_i32 s28, 0x7000
	s_mul_hi_u32 s29, s23, 0x7000
	v_add_co_u32_e32 v140, vcc, s87, v140
	s_add_i32 s29, s29, s28
	s_mulk_i32 s23, 0x7000
	v_addc_co_u32_e32 v141, vcc, 0, v141, vcc
	s_add_u32 s28, s92, s23
	v_add_co_u32_e32 v154, vcc, s5, v152
	s_addc_u32 s29, s93, s29
	s_max_i32 s23, s19, -6
	v_addc_co_u32_e32 v155, vcc, 0, v153, vcc
	s_add_i32 s23, s23, 6
	v_add_co_u32_e32 v152, vcc, s87, v152
	s_add_u32 s23, s0, s23
	s_nop 0
	v_addc_co_u32_e32 v153, vcc, 0, v153, vcc
	global_load_dword v172, v[130:131], off offset:2048
	global_load_dword v178, v[122:123], off
	global_load_dword v163, v[134:135], off offset:2048
	global_load_dword v164, v[132:133], off
	global_load_dword v149, v[150:151], off offset:2048
	s_nop 0
	global_load_dword v150, v[140:141], off
	global_load_dword v133, v[154:155], off offset:2048
	global_load_dword v135, v[152:153], off
	v_lshl_add_u64 v[122:123], s[28:29], 0, v[76:77]
	s_addc_u32 s28, s1, 0
	s_mulk_i32 s28, 0x7000
	s_mul_hi_u32 s29, s23, 0x7000
	s_add_i32 s29, s29, s28
	s_mulk_i32 s23, 0x7000
	s_add_u32 s28, s92, s23
	s_addc_u32 s29, s93, s29
	s_max_i32 s23, s19, -7
	s_add_i32 s23, s23, 7
	s_add_u32 s23, s0, s23
	v_lshl_add_u64 v[140:141], s[28:29], 0, v[76:77]
	s_addc_u32 s28, s1, 0
	s_mulk_i32 s28, 0x7000
	s_mul_hi_u32 s29, s23, 0x7000
	s_add_i32 s29, s29, s28
	s_mulk_i32 s23, 0x7000
	s_add_u32 s28, s92, s23
	s_addc_u32 s29, s93, s29
	s_max_i32 s23, s19, -8
	s_add_i32 s23, s23, 8
	v_add_co_u32_e32 v130, vcc, s5, v122
	s_add_u32 s23, s0, s23
	s_nop 0
	v_addc_co_u32_e32 v131, vcc, 0, v123, vcc
	v_lshl_add_u64 v[154:155], s[28:29], 0, v[76:77]
	s_addc_u32 s28, s1, 0
	v_add_co_u32_e32 v122, vcc, s87, v122
	s_mulk_i32 s28, 0x7000
	s_mul_hi_u32 s29, s23, 0x7000
	v_addc_co_u32_e32 v123, vcc, 0, v123, vcc
	s_add_i32 s29, s29, s28
	s_mulk_i32 s23, 0x7000
	v_add_co_u32_e32 v152, vcc, s5, v140
	s_add_u32 s28, s92, s23
	s_nop 0
	v_addc_co_u32_e32 v153, vcc, 0, v141, vcc
	s_addc_u32 s29, s93, s29
	s_max_i32 s23, s19, -9
	v_add_co_u32_e32 v140, vcc, s87, v140
	s_add_i32 s23, s23, 9
	s_nop 0
	v_addc_co_u32_e32 v141, vcc, 0, v141, vcc
	s_add_u32 s23, s0, s23
	v_add_co_u32_e32 v186, vcc, s5, v154
	v_lshl_add_u64 v[160:161], s[28:29], 0, v[76:77]
	s_addc_u32 s28, s1, 0
	v_addc_co_u32_e32 v187, vcc, 0, v155, vcc
	s_mulk_i32 s28, 0x7000
	s_mul_hi_u32 s29, s23, 0x7000
	v_add_co_u32_e32 v154, vcc, s87, v154
	s_add_i32 s29, s29, s28
	s_mulk_i32 s23, 0x7000
	v_addc_co_u32_e32 v155, vcc, 0, v155, vcc
	s_add_u32 s28, s92, s23
	v_add_co_u32_e32 v188, vcc, s5, v160
	s_addc_u32 s29, s93, s29
	s_max_i32 s23, s19, -10
	v_addc_co_u32_e32 v189, vcc, 0, v161, vcc
	s_add_i32 s23, s23, 10
	v_add_co_u32_e32 v190, vcc, s87, v160
	s_add_u32 s23, s0, s23
	s_nop 0
	v_addc_co_u32_e32 v191, vcc, 0, v161, vcc
	global_load_dword v159, v[130:131], off offset:2048
	global_load_dword v160, v[122:123], off
	global_load_dword v151, v[152:153], off offset:2048
	s_nop 0
	global_load_dword v152, v[140:141], off
	global_load_dword v139, v[186:187], off offset:2048
	s_nop 0
	global_load_dword v140, v[154:155], off
	global_load_dword v128, v[188:189], off offset:2048
	global_load_dword v130, v[190:191], off
	v_lshl_add_u64 v[122:123], s[28:29], 0, v[76:77]
	s_addc_u32 s28, s1, 0
	s_mulk_i32 s28, 0x7000
	s_mul_hi_u32 s29, s23, 0x7000
	s_add_i32 s29, s29, s28
	s_mulk_i32 s23, 0x7000
	s_add_u32 s28, s92, s23
	s_addc_u32 s29, s93, s29
	s_max_i32 s23, s19, -11
	s_add_i32 s23, s23, 11
	s_add_u32 s23, s0, s23
	v_lshl_add_u64 v[186:187], s[28:29], 0, v[76:77]
	s_addc_u32 s28, s1, 0
	s_mulk_i32 s28, 0x7000
	s_mul_hi_u32 s29, s23, 0x7000
	s_add_i32 s29, s29, s28
	s_mulk_i32 s23, 0x7000
	s_add_u32 s28, s92, s23
	s_addc_u32 s29, s93, s29
	s_max_i32 s23, s19, -12
	s_add_i32 s23, s23, 12
	v_add_co_u32_e32 v154, vcc, s5, v122
	s_add_u32 s23, s0, s23
	s_nop 0
	v_addc_co_u32_e32 v155, vcc, 0, v123, vcc
	v_lshl_add_u64 v[190:191], s[28:29], 0, v[76:77]
	s_addc_u32 s28, s1, 0
	v_add_co_u32_e32 v122, vcc, s87, v122
	s_mulk_i32 s28, 0x7000
	s_mul_hi_u32 s29, s23, 0x7000
	v_addc_co_u32_e32 v123, vcc, 0, v123, vcc
	s_add_i32 s29, s29, s28
	s_mulk_i32 s23, 0x7000
	v_add_co_u32_e32 v188, vcc, s5, v186
	s_add_u32 s28, s92, s23
	s_nop 0
	v_addc_co_u32_e32 v189, vcc, 0, v187, vcc
	s_addc_u32 s29, s93, s29
	s_max_i32 s23, s19, -13
	v_add_co_u32_e32 v186, vcc, s87, v186
	s_add_i32 s23, s23, 13
	s_nop 0
	v_addc_co_u32_e32 v187, vcc, 0, v187, vcc
	s_add_u32 s23, s0, s23
	v_add_co_u32_e32 v192, vcc, s5, v190
	v_lshl_add_u64 v[194:195], s[28:29], 0, v[76:77]
	s_addc_u32 s28, s1, 0
	v_addc_co_u32_e32 v193, vcc, 0, v191, vcc
	s_mulk_i32 s28, 0x7000
	s_mul_hi_u32 s29, s23, 0x7000
	v_add_co_u32_e32 v190, vcc, s87, v190
	s_add_i32 s29, s29, s28
	s_mulk_i32 s23, 0x7000
	v_addc_co_u32_e32 v191, vcc, 0, v191, vcc
	s_add_u32 s28, s92, s23
	v_add_co_u32_e32 v196, vcc, s5, v194
	s_addc_u32 s29, s93, s29
	s_max_i32 s23, s19, -14
	v_addc_co_u32_e32 v197, vcc, 0, v195, vcc
	s_add_i32 s23, s23, 14
	v_add_co_u32_e32 v194, vcc, s87, v194
	s_add_u32 s23, s0, s23
	s_nop 0
	v_addc_co_u32_e32 v195, vcc, 0, v195, vcc
	global_load_dword v161, v[154:155], off offset:2048
	global_load_dword v162, v[122:123], off
	global_load_dword v153, v[188:189], off offset:2048
	s_nop 0
	global_load_dword v154, v[186:187], off
	global_load_dword v141, v[192:193], off offset:2048
	global_load_dword v142, v[190:191], off
	global_load_dword v131, v[196:197], off offset:2048
	global_load_dword v132, v[194:195], off
	v_lshl_add_u64 v[122:123], s[28:29], 0, v[76:77]
	s_addc_u32 s28, s1, 0
	s_mulk_i32 s28, 0x7000
	s_mul_hi_u32 s29, s23, 0x7000
	s_add_i32 s29, s29, s28
	s_mulk_i32 s23, 0x7000
	s_add_u32 s28, s92, s23
	s_addc_u32 s29, s93, s29
	s_max_i32 s23, s19, -15
	v_add_co_u32_e32 v186, vcc, s5, v122
	s_add_i32 s23, s23, 15
	s_nop 0
	v_addc_co_u32_e32 v187, vcc, 0, v123, vcc
	s_add_u32 s23, s0, s23
	v_add_co_u32_e32 v122, vcc, s87, v122
	v_lshl_add_u64 v[188:189], s[28:29], 0, v[76:77]
	s_addc_u32 s28, s1, 0
	v_addc_co_u32_e32 v123, vcc, 0, v123, vcc
	s_mulk_i32 s28, 0x7000
	s_mul_hi_u32 s29, s23, 0x7000
	v_add_co_u32_e32 v190, vcc, s5, v188
	s_add_i32 s29, s29, s28
	s_mulk_i32 s23, 0x7000
	v_addc_co_u32_e32 v191, vcc, 0, v189, vcc
	s_add_u32 s28, s92, s23
	v_add_co_u32_e32 v188, vcc, s87, v188
	s_addc_u32 s29, s93, s29
	s_nop 0
	v_addc_co_u32_e32 v189, vcc, 0, v189, vcc
	v_lshl_add_u64 v[76:77], s[28:29], 0, v[76:77]
	v_add_co_u32_e32 v192, vcc, 0x2000, v76
	v_readfirstlane_b32 s23, v3
	s_nop 0
	v_addc_co_u32_e32 v193, vcc, 0, v77, vcc
	v_add_co_u32_e32 v76, vcc, 0x3000, v76
	v_readfirstlane_b32 s28, v2
	s_nop 0
	v_addc_co_u32_e32 v77, vcc, 0, v77, vcc
	global_load_dword v155, v[186:187], off offset:2048
	global_load_dword v156, v[122:123], off
	global_load_dword v145, v[190:191], off offset:2048
	global_load_dword v146, v[188:189], off
	global_load_dword v134, v[192:193], off offset:2048
	global_load_dword v137, v[76:77], off
	v_readfirstlane_b32 s29, v5
	s_cmpk_lt_i32 s22, 0x7e
	s_cbranch_scc1 .LBB0_633
	s_add_i32 s35, s19, 16
	s_max_u32 s46, s19, 0x7e2
	s_cmp_ge_u32 s46, s35
	s_cbranch_scc1 .LBB0_633
	v_readlane_b32 s48, v239, 60
	v_readlane_b32 s49, v239, 61
	s_add_u32 s47, s48, s14
	s_addc_u32 s15, s49, s15
	s_mul_i32 s15, s15, 0x1e000
	s_mul_hi_u32 s48, s47, 0x1e000
	s_add_i32 s15, s48, s15
	s_add_i32 s48, s46, 0xfffff81e
	s_ashr_i32 s49, s48, 31
	s_mul_i32 s47, s47, 0x1e000
	s_lshl_b64 s[48:49], s[48:49], 12
	s_add_u32 s47, s47, s48
	s_addc_u32 s15, s15, s49
	v_readlane_b32 s48, v241, 41
	s_add_u32 s48, s48, s47
	v_readlane_b32 s47, v241, 42
	s_addc_u32 s49, s47, s15
	s_cmpk_gt_u32 s19, 0x7e2
	s_cselect_b32 s47, s19, 0x7e2
	v_lshl_add_u64 v[2:3], v[6:7], 2, s[48:49]
	s_mul_hi_i32 s15, s14, 0x3800000
	s_mul_i32 s14, s14, 0x3800000
	s_mul_hi_u32 s48, s47, 0x7000
	s_mulk_i32 s47, 0x7000
	s_add_u32 s14, s14, s47
	s_addc_u32 s15, s15, s48
	v_readlane_b32 s47, v241, 43
	s_add_u32 s14, s47, s14
	v_readlane_b32 s47, v241, 44
	s_addc_u32 s15, s47, s15
	v_lshl_add_u64 v[4:5], v[6:7], 1, s[14:15]

.LBB0_646:
	s_or_b64 exec, exec, s[0:1]
	s_mov_b64 s[0:1], 0x1bfff
	s_mov_b32 s28, 0x90000
	s_mov_b32 s29, 0x80000
	s_mov_b32 s34, 0xa0000
	v_cmp_lt_u64_e32 vcc, s[0:1], v[2:3]
	s_and_saveexec_b64 s[0:1], vcc
	v_readlane_b32 s22, v241, 39
	s_mov_b32 s18, 0x10000
	v_readlane_b32 s23, v241, 40
	s_mov_b32 s19, 0x8000
	s_cbranch_execz .LBB0_623
	v_readlane_b32 s10, v244, 20
	v_lshlrev_b32_e32 v172, 2, v124
	v_readlane_b32 s11, v244, 21
	v_lshlrev_b64 v[6:7], 8, v[18:19]
	s_nop 0
	v_lshl_add_u64 v[4:5], s[10:11], 0, v[172:173]
	v_readlane_b32 s10, v241, 33
	v_readlane_b32 s11, v241, 34
	s_nop 1
	v_lshl_add_u64 v[6:7], s[10:11], 0, v[6:7]
	v_readlane_b32 s10, v241, 47
	s_nop 1
	v_lshl_add_u32 v12, v18, 1, s10
	s_mov_b64 s[10:11], 0
